# WIN epilogue: every 16x64B fragment store transposed through a per-wave 1KB LDS slot so 4 consecutive lanes write one contiguous 64B row segment (coalesced stores)
# speedup vs baseline: 1.0033x; 1.0026x over previous
; #define PG8_STAGE(bufoff, gbase, voff) do { _Pragma("unroll") for (int _i = 0; _i < 2; ++_i) \
;         __builtin_amdgcn_global_load_lds((const unsigned*)((const char*)(gbase) + (voff)[_i]), (PG8_LAS unsigned*)(lds + (bufoff) + ldsw + _i * 8192), 16, 0, 0); } while (0)
; #define PG8_WAIT_V(n) asm volatile("s_waitcnt vmcnt(" #n ")" ::: "memory")
; #define PG8_BAR __builtin_amdgcn_s_barrier()
; template <class Epi, class Sched, bool ALIGN_EPI = false, bool SP2 = false>
; __device__ __forceinline__ void gemm_phase(PG8_LAS unsigned char* lds, const Gemm g, const Sched& S, const Epi& E) {
;     ...
;     for (int i = 0; i < 2; ++i) { int R, C; stage_rc(tid * 16 + i * 8192, R, C); const int Rb = Epi::PERM ? ((R & ~31) + perm32(R & 31)) : R;
;         voffA[i] = (unsigned)(R * K + C) * 2u; voffB[i] = (unsigned)(Rb * K + C) * 2u; }
;     const size_t kstep = (size_t)(BK * 2);
;     const size_t hstep = (size_t)HALF * K * 2;
;     const size_t tstep = 2 * hstep;
;     const unsigned ldsw = (unsigned)wid * 1024u;
;     const int aoff = lds_byte(wr * 64 + fr, fq * 8), boff = lds_byte(wc * 32 + fr, fq * 8);
;     ...
;         PG8_WAIT_V(2); PG8_BAR;
;         PG8_STAGE(PG8_SB(1, 0), cB + kstep, voffB); PG8_STAGE(PG8_SA(1, 0), cA + kstep, voffA); PG8_STAGE(PG8_SB(1, 1), cB + hstep + kstep, voffB);
;         PG8_WAIT_V(6); PG8_BAR;
.LBB0_618:
	v_readlane_b32 s12, v253, 49
	v_mov_b32_e32 v133, v187
	v_readlane_b32 s13, v253, 50
	v_mov_b32_e32 v129, v187
	s_add_i32 m0, s46, 0x18000
	v_lshl_add_u64 v[12:13], s[12:13], 0, v[132:133]
	v_lshl_add_u64 v[14:15], s[12:13], 0, v[128:129]
	v_lshl_add_u64 v[12:13], v[12:13], 0, s[92:93]
	s_waitcnt vmcnt(2)
	s_barrier
	global_load_lds_dwordx4 v[12:13], off
	v_lshl_add_u64 v[12:13], v[14:15], 0, s[92:93]
	s_add_i32 m0, s46, 0x1a000
	s_add_i32 s49, s46, 0x8000
	global_load_lds_dwordx4 v[12:13], off
	v_lshl_add_u64 v[0:1], v[0:1], 0, s[92:93]
	s_mov_b32 m0, s49
	s_add_i32 s50, s46, 0xa000
	v_readlane_b32 s8, v253, 51
	global_load_lds_dwordx4 v[0:1], off
	v_lshl_add_u64 v[0:1], v[2:3], 0, s[92:93]
	s_mov_b32 m0, s50
	v_readlane_b32 s9, v253, 52
	global_load_lds_dwordx4 v[0:1], off
	s_add_i32 m0, s46, 0x1c000
	v_lshl_add_u64 v[0:1], s[8:9], 0, v[132:133]
	global_load_lds_dwordx4 v[0:1], off
	v_lshl_add_u64 v[0:1], s[8:9], 0, v[128:129]
	s_add_i32 m0, s46, 0x1e000
	s_and_b32 s6, s6, 3
	global_load_lds_dwordx4 v[0:1], off
	v_lshrrev_b32_e32 v0, 1, v6
	v_and_b32_e32 v0, 24, v0
	v_and_b32_e32 v1, 15, v6
	v_lshlrev_b32_e32 v2, 1, v0
	v_lshl_or_b32 v137, s3, 6, v1
	v_lshl_or_b32 v1, v1, 6, v2
	v_lshlrev_b32_e32 v2, 2, v6
	s_lshl_b32 s3, s3, 13
	v_and_b32_e32 v2, 32, v2
	v_bitop3_b32 v3, v1, s3, v2 bitop3:0xde
	s_lshl_b32 s3, s6, 12
	v_bitop3_b32 v156, v1, s3, v2 bitop3:0xde
	v_lshlrev_b32_e32 v1, 14, v9
	v_and_b32_e32 v1, 0xffff8000, v1
	v_lshl_add_u32 v1, v8, 11, v1
	v_and_b32_e32 v2, 1, v9
	v_lshl_or_b32 v1, v2, 6, v1
	v_readlane_b32 s2, v252, 13
	v_lshl_add_u32 v140, v10, 1, v1
	v_lshlrev_b32_e32 v1, 14, v4
	s_cmpk_lt_u32 s0, 0x100
	v_lshlrev_b32_e32 v186, 2, v0
	v_readlane_b32 s3, v252, 14
	v_and_b32_e32 v1, 0xffff8000, v1
	s_waitcnt vmcnt(6)
	s_cselect_b64 s[20:21], -1, 0
	s_cmp_gt_u32 s6, 1
	v_lshl_add_u64 v[138:139], s[2:3], 0, v[186:187]
	v_lshl_add_u32 v1, v5, 11, v1
	v_and_b32_e32 v2, 1, v4
	v_readlane_b32 s2, v253, 41
	s_cselect_b64 s[22:23], -1, 0
	s_lshl_b32 s51, s6, 6
	v_lshl_or_b32 v1, v2, 6, v1
	v_readlane_b32 s3, v253, 42
	v_lshl_or_b32 v136, s6, 5, v0
	s_or_b32 s52, s51, 0xfffffc00
	v_mov_b32_e32 v141, v187
	v_lshl_add_u32 v142, v7, 1, v1
	v_mov_b32_e32 v143, v187
	s_mov_b32 s53, 0
	v_add_u32_e32 v157, 0, v3
	v_lshlrev_b32_e32 v186, 1, v0
	v_and_b32_e32 v244, 63, v200
	v_and_b32_e32 v245, 15, v200
	v_bfe_u32 v243, v200, 4, 2
	v_lshrrev_b32_e32 v248, 2, v244
	v_sub_u32_e32 v248, v248, v245
	v_and_b32_e32 v249, 3, v244
	v_sub_u32_e32 v249, v249, v243
	v_and_b32_e32 v249, 3, v249
	v_sub_u32_e32 v249, v249, v243
	v_lshlrev_b32_e32 v249, 4, v249
	v_lshrrev_b32_e32 v242, 6, v200
	v_lshlrev_b32_e32 v242, 10, v242
	v_add_u32_e32 v242, 0x20400, v242
	v_lshl_add_u32 v247, v244, 4, v242
	v_lshrrev_b32_e32 v241, 2, v245
	v_add_u32_e32 v241, v241, v243
	v_and_b32_e32 v241, 3, v241
	v_lshl_add_u32 v246, v245, 6, v242
	v_lshl_add_u32 v246, v241, 4, v246
	v_readlane_b32 s0, v253, 10
	s_mov_b32 s3, s2
	s_barrier
	s_branch .LBB0_621

; DI float sigmoidf_(float v) { return __builtin_amdgcn_rcpf(1.f + __builtin_amdgcn_exp2f(-v * 1.4426950408889634f)); }
;   DI void operator()(const f32x4 (&acc)[2][2][4][2], const Unit& u, int wr, int wc, int fr, int fq) const {
;     ...
;           const int rowl = rowl0 + ai * 128 + m * 16;
;           const float rstd = rsqrtf(ssq[row_off + rowl] * (1.f / DM) + EPSN) * (mode == 1 ? QSCALE : 1.f);
; #pragma unroll
;           for (int bj = 0; bj < 2; ++bj) {
;             const int col = bj * 128 + c8;
;             if (tl == 19 && col >= 64) continue;
;             f32x4 v0 = acc[ai][bj][m][0] * rstd, v1 = acc[ai][bj][m][1] * rstd;
;             if (mode == 2) {
; #pragma unroll
;               for (int e = 0; e < 4; ++e) { v0[e] = sigmoidf_(v0[e]); v1[e] = sigmoidf_(v1[e]); }
;             }
.LBB0_651:
	v_mul_i32_i24_e64 v250, v248, s36
	v_lshl_add_u32 v250, v250, 1, v249
	v_ashrrev_i32_e32 v251, 31, v250
	v_readlane_b32 s2, v255, 32
	v_ashrrev_i32_e32 v147, 31, v158
	v_mul_lo_u32 v159, s36, v147
	v_add_u32_e32 v144, s2, v158
	v_ashrrev_i32_e32 v145, 31, v144
	v_lshl_add_u64 v[144:145], v[144:145], 2, s[4:5]
	global_load_dword v146, v[144:145], off
	s_xor_b64 s[10:11], s[10:11], -1
	s_cmp_lg_u32 s0, 19
	s_cselect_b64 s[40:41], -1, 0
	s_cmp_eq_u32 s0, 19
	s_cselect_b64 s[54:55], -1, 0
	s_ashr_i32 s15, s14, 31
	v_mad_u64_u32 v[144:145], s[38:39], s36, v158, 0
	s_lshl_b64 s[14:15], s[14:15], 1
	s_add_u32 s38, s12, s14
	v_mul_lo_u32 v148, s37, v158
	s_addc_u32 s39, s13, s15
	s_and_b64 s[14:15], s[54:55], s[22:23]
	v_cndmask_b32_e64 v149, 0, 1, s[10:11]
	v_add3_u32 v145, v145, v159, v148
	s_and_b64 s[12:13], exec, s[14:15]
	v_cmp_ne_u32_e64 s[10:11], 1, v149
	v_lshl_add_u64 v[144:145], v[144:145], 1, s[38:39]
	s_waitcnt vmcnt(0)
	v_fmamk_f32 v146, v146, 0x3a800000, v203
	v_mul_f32_e32 v147, 0x4b800000, v146
	v_cmp_gt_f32_e32 vcc, s82, v146
	s_nop 1
	v_cndmask_b32_e32 v146, v146, v147, vcc
	v_rsq_f32_e32 v146, v146
	s_nop 0
	v_mul_f32_e32 v147, 0x45800000, v146
	v_cndmask_b32_e32 v146, v146, v147, vcc
	v_mul_f32_e32 v146, s3, v146
	v_mov_b32_e32 v147, v146
	s_mov_b64 vcc, s[12:13]
	s_cbranch_vccnz .LBB0_657
	v_mov_b32_e32 v150, v146
	v_mov_b32_e32 v151, v146
	v_pk_mul_f32 v[148:149], v[126:127], v[150:151]
	v_pk_mul_f32 v[152:153], v[124:125], v[146:147]
	v_pk_mul_f32 v[150:151], v[122:123], v[150:151]
	v_pk_mul_f32 v[154:155], v[120:121], v[146:147]
	s_and_b64 vcc, exec, s[10:11]
	s_mov_b64 s[12:13], -1
	s_cbranch_vccnz .LBB0_654
	s_mov_b64 s[12:13], 0

; DI float sigmoidf_(float v) { return __builtin_amdgcn_rcpf(1.f + __builtin_amdgcn_exp2f(-v * 1.4426950408889634f)); }
; DI u32x4 pack8(f32x4 a, f32x4 b) { u32x4 w; w.x = cvtpk(a[0], a[1]); w.y = cvtpk(a[2], a[3]); w.z = cvtpk(b[0], b[1]); w.w = cvtpk(b[2], b[3]); return w; }
;   DI void operator()(const f32x4 (&acc)[2][2][4][2], const Unit& u, int wr, int wc, int fr, int fq) const {
;     ...
;             f32x4 v0 = acc[ai][bj][m][0] * rstd, v1 = acc[ai][bj][m][1] * rstd;
;             if (mode == 2) {
; #pragma unroll
;               for (int e = 0; e < 4; ++e) { v0[e] = sigmoidf_(v0[e]); v1[e] = sigmoidf_(v1[e]); }
;             }
;             if (tl >= 20) __builtin_nontemporal_store(pack8(v0, v1), (u32x4*)(dst + (size_t)rowl * pitch + coloff + col));
;             else *(u32x4*)(dst + (size_t)rowl * pitch + coloff + col) = pack8(v0, v1);
.LBB0_656:
	v_cvt_pk_bf16_f32 v152, v152, v153
	v_cvt_pk_bf16_f32 v153, v148, v149
	v_lshlrev_b32_e32 v148, 1, v136
	v_mov_b32_e32 v149, v187
	v_cvt_pk_bf16_f32 v154, v154, v155
	v_cvt_pk_bf16_f32 v155, v150, v151
	v_lshl_add_u64 v[148:149], v[144:145], 0, v[148:149]
	ds_write_b128 v246, v[152:155]
	v_lshl_add_u64 v[240:241], v[148:149], 0, v[250:251]
	ds_read_b128 v[232:235], v247
	s_waitcnt lgkmcnt(0)
	global_store_dwordx4 v[240:241], v[232:235], off

; DI float sigmoidf_(float v) { return __builtin_amdgcn_rcpf(1.f + __builtin_amdgcn_exp2f(-v * 1.4426950408889634f)); }
; DI u32x4 pack8(f32x4 a, f32x4 b) { u32x4 w; w.x = cvtpk(a[0], a[1]); w.y = cvtpk(a[2], a[3]); w.z = cvtpk(b[0], b[1]); w.w = cvtpk(b[2], b[3]); return w; }
;   DI void operator()(const f32x4 (&acc)[2][2][4][2], const Unit& u, int wr, int wc, int fr, int fq) const {
;     ...
;             f32x4 v0 = acc[ai][bj][m][0] * rstd, v1 = acc[ai][bj][m][1] * rstd;
;             if (mode == 2) {
; #pragma unroll
;               for (int e = 0; e < 4; ++e) { v0[e] = sigmoidf_(v0[e]); v1[e] = sigmoidf_(v1[e]); }
;             }
;             if (tl >= 20) __builtin_nontemporal_store(pack8(v0, v1), (u32x4*)(dst + (size_t)rowl * pitch + coloff + col));
;             else *(u32x4*)(dst + (size_t)rowl * pitch + coloff + col) = pack8(v0, v1);
.LBB0_662:
	v_cvt_pk_bf16_f32 v154, v146, v147
	v_lshlrev_b32_e32 v146, 1, v136
	v_mov_b32_e32 v147, v187
	v_cvt_pk_bf16_f32 v152, v152, v153
	v_cvt_pk_bf16_f32 v153, v148, v149
	v_cvt_pk_bf16_f32 v155, v150, v151
	v_lshl_add_u64 v[144:145], v[144:145], 0, v[146:147]
	ds_write_b128 v246, v[152:155]
	v_lshl_add_u64 v[240:241], v[144:145], 0, v[250:251]
	ds_read_b128 v[232:235], v247
	s_waitcnt lgkmcnt(0)
	global_store_dwordx4 v[240:241], v[232:235], off offset:256

; DI u32x4 pack8(f32x4 a, f32x4 b) { u32x4 w; w.x = cvtpk(a[0], a[1]); w.y = cvtpk(a[2], a[3]); w.z = cvtpk(b[0], b[1]); w.w = cvtpk(b[2], b[3]); return w; }
;   DI void operator()(const f32x4 (&acc)[2][2][4][2], const Unit& u, int wr, int wc, int fr, int fq) const {
;     ...
;           const int rowl = rowl0 + ai * 128 + m * 16; const int t = rowl & (SEQ - 1);
;           const float rstd = rsqrtf(ssq[row_off + rowl] * (1.f / DM) + EPSN) * sc;
;           const float* rc = rope + t * 32 + 8 * fq;
;           const f32x4 c0 = *(const f32x4*)(rc), c1 = *(const f32x4*)(rc + 4), s0 = *(const f32x4*)(rc + 65536), s1 = *(const f32x4*)(rc + 65536 + 4);
;           const f32x4 x1a = acc[ai][0][m][0] * rstd, x1b = acc[ai][0][m][1] * rstd, x2a = acc[ai][1][m][0] * rstd, x2b = acc[ai][1][m][1] * rstd;
;           const f32x4 o1a = x1a * c0 - x2a * s0, o1b = x1b * c1 - x2b * s1, o2a = x2a * c0 + x1a * s0, o2b = x2b * c1 + x1b * s1;
;           bf16_t* d = dst + (size_t)rowl * pitch + colbase + 8 * fq;
;           *(u32x4*)(d) = pack8(o1a, o1b); *(u32x4*)(d + 32) = pack8(o2a, o2b);
.LBB0_756:
	v_mul_i32_i24_e64 v250, v248, s10
	v_lshl_add_u32 v250, v250, 1, v249
	v_ashrrev_i32_e32 v251, 31, v250
	v_readlane_b32 s2, v255, 32
	s_ashr_i32 s13, s12, 31
	s_lshl_b64 s[12:13], s[12:13], 1
	v_add_u32_e32 v146, s2, v158
	v_ashrrev_i32_e32 v147, 31, v146
	v_lshl_add_u64 v[146:147], v[146:147], 2, s[4:5]
	global_load_dword v146, v[146:147], off
	s_add_u32 s12, s14, s12
	s_addc_u32 s13, s15, s13
	s_mov_b64 s[14:15], 0x40000
	s_mov_b32 s0, 0x40000
	v_lshl_add_u64 v[144:145], s[12:13], 0, v[186:187]
	s_waitcnt vmcnt(0)
	v_fmamk_f32 v146, v146, 0x3a800000, v203
	v_cmp_gt_f32_e32 vcc, s82, v146
	v_mul_f32_e32 v147, 0x4b800000, v146
	s_nop 0
	v_cndmask_b32_e32 v146, v146, v147, vcc
	v_rsq_f32_e32 v146, v146
	s_nop 0
	v_mul_f32_e32 v147, 0x45800000, v146
	v_cndmask_b32_e32 v146, v146, v147, vcc
	v_mul_f32_e32 v154, s3, v146
	v_lshlrev_b32_e32 v146, 7, v158
	v_and_b32_e32 v146, 0x3e780, v146
	v_mov_b32_e32 v147, v187
	v_lshl_add_u64 v[160:161], v[138:139], 0, v[146:147]
	global_load_dwordx4 v[146:149], v[160:161], off offset:16
	global_load_dwordx4 v[150:153], v[160:161], off
	v_lshl_add_u64 v[164:165], v[160:161], 0, s[14:15]
	v_add_co_u32_e32 v160, vcc, s0, v160
	v_pk_mul_f32 v[116:117], v[116:117], v[154:155] op_sel_hi:[1,0]
	s_nop 0
	v_addc_co_u32_e32 v161, vcc, 0, v161, vcc
	global_load_dwordx4 v[160:163], v[160:161], off
	s_nop 0
	global_load_dwordx4 v[164:167], v[164:165], off offset:16
	v_pk_mul_f32 v[124:125], v[124:125], v[154:155] op_sel_hi:[1,0]
	v_pk_mul_f32 v[126:127], v[126:127], v[154:155] op_sel_hi:[1,0]
	v_pk_mul_f32 v[120:121], v[120:121], v[154:155] op_sel_hi:[1,0]
	v_pk_mul_f32 v[122:123], v[122:123], v[154:155] op_sel_hi:[1,0]
	v_pk_mul_f32 v[118:119], v[118:119], v[154:155] op_sel_hi:[1,0]
	v_pk_mul_f32 v[114:115], v[114:115], v[154:155] op_sel_hi:[1,0]
	v_pk_mul_f32 v[112:113], v[112:113], v[154:155] op_sel_hi:[1,0]
	s_waitcnt vmcnt(1)
	v_pk_mul_f32 v[154:155], v[160:161], v[116:117]
	s_nop 0
	v_pk_fma_f32 v[154:155], v[150:151], v[124:125], v[154:155] neg_lo:[0,0,1] neg_hi:[0,0,1]
	v_pk_mul_f32 v[124:125], v[160:161], v[124:125]
	s_waitcnt vmcnt(0)
	v_pk_mul_f32 v[170:171], v[164:165], v[112:113]
	v_pk_mul_f32 v[172:173], v[166:167], v[114:115]
	v_pk_fma_f32 v[124:125], v[150:151], v[116:117], v[124:125]
	v_pk_mul_f32 v[116:117], v[164:165], v[120:121]
	v_pk_fma_f32 v[172:173], v[148:149], v[122:123], v[172:173] neg_lo:[0,0,1] neg_hi:[0,0,1]
	v_pk_fma_f32 v[170:171], v[146:147], v[120:121], v[170:171] neg_lo:[0,0,1] neg_hi:[0,0,1]
	v_pk_mul_f32 v[120:121], v[166:167], v[122:123]
	v_pk_fma_f32 v[122:123], v[146:147], v[112:113], v[116:117]
	v_ashrrev_i32_e32 v112, 31, v158
	v_pk_mul_f32 v[168:169], v[162:163], v[118:119]
	v_pk_fma_f32 v[120:121], v[148:149], v[114:115], v[120:121]
	v_mul_lo_u32 v113, s11, v158
	v_mul_lo_u32 v112, s10, v112
	v_mad_u64_u32 v[114:115], s[12:13], s10, v158, 0
	v_pk_fma_f32 v[168:169], v[152:153], v[126:127], v[168:169] neg_lo:[0,0,1] neg_hi:[0,0,1]
	v_pk_mul_f32 v[126:127], v[162:163], v[126:127]
	v_add3_u32 v115, v115, v112, v113
	v_pk_fma_f32 v[118:119], v[152:153], v[118:119], v[126:127]
	v_lshl_add_u64 v[126:127], v[114:115], 1, v[144:145]
	v_cvt_pk_bf16_f32 v114, v154, v155
	v_cvt_pk_bf16_f32 v115, v168, v169
	v_cvt_pk_bf16_f32 v116, v170, v171
	v_cvt_pk_bf16_f32 v117, v172, v173
	ds_write_b128 v246, v[114:117]
	v_lshl_add_u64 v[240:241], v[126:127], 0, v[250:251]
	ds_read_b128 v[232:235], v247
	s_waitcnt lgkmcnt(0)
	global_store_dwordx4 v[240:241], v[232:235], off
	v_or_b32_e32 v113, 16, v158
	s_nop 0
	v_cvt_pk_bf16_f32 v114, v124, v125
	v_cvt_pk_bf16_f32 v115, v118, v119
	v_cvt_pk_bf16_f32 v116, v122, v123
	v_cvt_pk_bf16_f32 v117, v120, v121
	ds_write_b128 v246, v[114:117]
	v_lshl_add_u64 v[240:241], v[126:127], 0, v[250:251]
	ds_read_b128 v[232:235], v247
	s_waitcnt lgkmcnt(0)
	global_store_dwordx4 v[240:241], v[232:235], off offset:64
	s_nop 1
	v_add_u32_e32 v114, s2, v113
	v_ashrrev_i32_e32 v115, 31, v114
	v_lshl_add_u64 v[114:115], v[114:115], 2, s[4:5]
	global_load_dword v114, v[114:115], off
	s_waitcnt vmcnt(0)
	v_fmamk_f32 v114, v114, 0x3a800000, v203
	v_cmp_gt_f32_e32 vcc, s82, v114
	v_mul_f32_e32 v115, 0x4b800000, v114
	s_nop 0
	v_cndmask_b32_e32 v114, v114, v115, vcc
	v_rsq_f32_e32 v114, v114
	s_nop 0
	v_mul_f32_e32 v115, 0x45800000, v114
	v_cndmask_b32_e32 v114, v114, v115, vcc
	v_mul_f32_e32 v126, s3, v114
	v_lshlrev_b32_e32 v114, 7, v113
	v_and_b32_e32 v114, 0x3ef80, v114
	v_mov_b32_e32 v115, v187
	v_lshl_add_u64 v[122:123], v[138:139], 0, v[114:115]
	global_load_dwordx4 v[114:117], v[122:123], off offset:16
	global_load_dwordx4 v[118:121], v[122:123], off
	v_lshl_add_u64 v[146:147], v[122:123], 0, s[14:15]
	v_add_co_u32_e32 v122, vcc, s0, v122
	v_pk_mul_f32 v[98:99], v[98:99], v[126:127] op_sel_hi:[1,0]
	s_nop 0
	v_addc_co_u32_e32 v123, vcc, 0, v123, vcc
	global_load_dwordx4 v[122:125], v[122:123], off
	s_nop 0
	global_load_dwordx4 v[146:149], v[146:147], off offset:16
	v_pk_mul_f32 v[96:97], v[96:97], v[126:127] op_sel_hi:[1,0]
	v_pk_mul_f32 v[104:105], v[104:105], v[126:127] op_sel_hi:[1,0]
	v_pk_mul_f32 v[106:107], v[106:107], v[126:127] op_sel_hi:[1,0]
	v_pk_mul_f32 v[102:103], v[102:103], v[126:127] op_sel_hi:[1,0]
	v_pk_mul_f32 v[100:101], v[100:101], v[126:127] op_sel_hi:[1,0]
	v_pk_mul_f32 v[108:109], v[108:109], v[126:127] op_sel_hi:[1,0]
	v_pk_mul_f32 v[110:111], v[110:111], v[126:127] op_sel_hi:[1,0]
	s_waitcnt vmcnt(1)
	v_pk_mul_f32 v[126:127], v[122:123], v[100:101]
	s_waitcnt vmcnt(0)
; DI u32x4 pack8(f32x4 a, f32x4 b) { u32x4 w; w.x = cvtpk(a[0], a[1]); w.y = cvtpk(a[2], a[3]); w.z = cvtpk(b[0], b[1]); w.w = cvtpk(b[2], b[3]); return w; }
;   DI void operator()(const f32x4 (&acc)[2][2][4][2], const Unit& u, int wr, int wc, int fr, int fq) const {
;     ...
; #pragma unroll
;       for (int ai = 0; ai < 2; ++ai)
; #pragma unroll
;         for (int m = 0; m < 4; ++m) {
;           const int rowl = rowl0 + ai * 128 + m * 16; const int t = rowl & (SEQ - 1);
;           const float rstd = rsqrtf(ssq[row_off + rowl] * (1.f / DM) + EPSN) * sc;
;           const float* rc = rope + t * 32 + 8 * fq;
;           const f32x4 c0 = *(const f32x4*)(rc), c1 = *(const f32x4*)(rc + 4), s0 = *(const f32x4*)(rc + 65536), s1 = *(const f32x4*)(rc + 65536 + 4);
;           const f32x4 x1a = acc[ai][0][m][0] * rstd, x1b = acc[ai][0][m][1] * rstd, x2a = acc[ai][1][m][0] * rstd, x2b = acc[ai][1][m][1] * rstd;
;           const f32x4 o1a = x1a * c0 - x2a * s0, o1b = x1b * c1 - x2b * s1, o2a = x2a * c0 + x1a * s0, o2b = x2b * c1 + x1b * s1;
;           bf16_t* d = dst + (size_t)rowl * pitch + colbase + 8 * fq;
;           *(u32x4*)(d) = pack8(o1a, o1b); *(u32x4*)(d + 32) = pack8(o2a, o2b);
;           asm volatile("" ::: "memory");
;         }
	v_pk_mul_f32 v[152:153], v[146:147], v[96:97]
	v_pk_mul_f32 v[154:155], v[148:149], v[98:99]
	v_pk_fma_f32 v[152:153], v[114:115], v[104:105], v[152:153] neg_lo:[0,0,1] neg_hi:[0,0,1]
	v_pk_fma_f32 v[154:155], v[116:117], v[106:107], v[154:155] neg_lo:[0,0,1] neg_hi:[0,0,1]
	v_pk_mul_f32 v[104:105], v[146:147], v[104:105]
	v_pk_mul_f32 v[106:107], v[148:149], v[106:107]
	v_pk_mul_f32 v[150:151], v[124:125], v[102:103]
	v_pk_fma_f32 v[106:107], v[116:117], v[98:99], v[106:107]
	v_pk_fma_f32 v[104:105], v[114:115], v[96:97], v[104:105]
	v_mul_lo_u32 v98, s11, v113
	v_mad_u64_u32 v[96:97], s[12:13], s10, v113, 0
	v_pk_fma_f32 v[150:151], v[120:121], v[110:111], v[150:151] neg_lo:[0,0,1] neg_hi:[0,0,1]
	v_pk_fma_f32 v[126:127], v[118:119], v[108:109], v[126:127] neg_lo:[0,0,1] neg_hi:[0,0,1]
	v_pk_mul_f32 v[108:109], v[122:123], v[108:109]
	v_pk_mul_f32 v[110:111], v[124:125], v[110:111]
	v_add3_u32 v97, v97, v112, v98
	v_pk_fma_f32 v[102:103], v[120:121], v[102:103], v[110:111]
	v_pk_fma_f32 v[100:101], v[118:119], v[100:101], v[108:109]
	v_lshl_add_u64 v[108:109], v[96:97], 1, v[144:145]
	v_cvt_pk_bf16_f32 v96, v126, v127
	v_cvt_pk_bf16_f32 v97, v150, v151
	v_cvt_pk_bf16_f32 v98, v152, v153
	v_cvt_pk_bf16_f32 v99, v154, v155
	ds_write_b128 v246, v[96:99]
	v_lshl_add_u64 v[240:241], v[108:109], 0, v[250:251]
	ds_read_b128 v[232:235], v247
	s_waitcnt lgkmcnt(0)
	global_store_dwordx4 v[240:241], v[232:235], off
	v_or_b32_e32 v113, 32, v158
	s_nop 0
	v_cvt_pk_bf16_f32 v96, v100, v101
	v_cvt_pk_bf16_f32 v97, v102, v103
	v_cvt_pk_bf16_f32 v98, v104, v105
	v_cvt_pk_bf16_f32 v99, v106, v107
	ds_write_b128 v246, v[96:99]
	v_lshl_add_u64 v[240:241], v[108:109], 0, v[250:251]
	ds_read_b128 v[232:235], v247
	s_waitcnt lgkmcnt(0)
	global_store_dwordx4 v[240:241], v[232:235], off offset:64
	s_nop 1
	v_add_u32_e32 v96, s2, v113
	v_ashrrev_i32_e32 v97, 31, v96
	v_lshl_add_u64 v[96:97], v[96:97], 2, s[4:5]
	global_load_dword v96, v[96:97], off
	s_waitcnt vmcnt(0)
	v_fmamk_f32 v96, v96, 0x3a800000, v203
	v_cmp_gt_f32_e32 vcc, s82, v96
	v_mul_f32_e32 v97, 0x4b800000, v96
	s_nop 0
	v_cndmask_b32_e32 v96, v96, v97, vcc
	v_rsq_f32_e32 v96, v96
	s_nop 0
	v_mul_f32_e32 v97, 0x45800000, v96
	v_cndmask_b32_e32 v96, v96, v97, vcc
	v_mul_f32_e32 v114, s3, v96
	v_lshlrev_b32_e32 v96, 7, v113
	v_and_b32_e32 v96, 0x3f780, v96
	v_mov_b32_e32 v97, v187
	v_lshl_add_u64 v[104:105], v[138:139], 0, v[96:97]
	global_load_dwordx4 v[96:99], v[104:105], off offset:16
	global_load_dwordx4 v[100:103], v[104:105], off
	v_lshl_add_u64 v[108:109], v[104:105], 0, s[14:15]
	v_add_co_u32_e32 v104, vcc, s0, v104
	v_pk_mul_f32 v[82:83], v[82:83], v[114:115] op_sel_hi:[1,0]
	s_nop 0
	v_addc_co_u32_e32 v105, vcc, 0, v105, vcc
	global_load_dwordx4 v[104:107], v[104:105], off
	s_nop 0
	global_load_dwordx4 v[108:111], v[108:109], off offset:16
	v_pk_mul_f32 v[80:81], v[80:81], v[114:115] op_sel_hi:[1,0]
	v_pk_mul_f32 v[88:89], v[88:89], v[114:115] op_sel_hi:[1,0]
	v_pk_mul_f32 v[90:91], v[90:91], v[114:115] op_sel_hi:[1,0]
	v_pk_mul_f32 v[86:87], v[86:87], v[114:115] op_sel_hi:[1,0]
	v_pk_mul_f32 v[84:85], v[84:85], v[114:115] op_sel_hi:[1,0]
	v_pk_mul_f32 v[92:93], v[92:93], v[114:115] op_sel_hi:[1,0]
	v_pk_mul_f32 v[94:95], v[94:95], v[114:115] op_sel_hi:[1,0]
	s_waitcnt vmcnt(1)
	v_pk_mul_f32 v[114:115], v[104:105], v[84:85]
	s_waitcnt vmcnt(0)
	v_pk_mul_f32 v[118:119], v[108:109], v[80:81]
	v_pk_mul_f32 v[120:121], v[110:111], v[82:83]
	v_pk_fma_f32 v[118:119], v[96:97], v[88:89], v[118:119] neg_lo:[0,0,1] neg_hi:[0,0,1]
	v_pk_fma_f32 v[120:121], v[98:99], v[90:91], v[120:121] neg_lo:[0,0,1] neg_hi:[0,0,1]
	v_pk_mul_f32 v[88:89], v[108:109], v[88:89]
	v_pk_mul_f32 v[90:91], v[110:111], v[90:91]
	v_pk_mul_f32 v[116:117], v[106:107], v[86:87]
	v_pk_fma_f32 v[90:91], v[98:99], v[82:83], v[90:91]
	v_pk_fma_f32 v[88:89], v[96:97], v[80:81], v[88:89]
	v_mul_lo_u32 v82, s11, v113
	v_mad_u64_u32 v[80:81], s[12:13], s10, v113, 0
	v_pk_fma_f32 v[116:117], v[102:103], v[94:95], v[116:117] neg_lo:[0,0,1] neg_hi:[0,0,1]
	v_pk_fma_f32 v[114:115], v[100:101], v[92:93], v[114:115] neg_lo:[0,0,1] neg_hi:[0,0,1]
	v_pk_mul_f32 v[92:93], v[104:105], v[92:93]
	v_pk_mul_f32 v[94:95], v[106:107], v[94:95]
	v_add3_u32 v81, v81, v112, v82
	v_pk_fma_f32 v[86:87], v[102:103], v[86:87], v[94:95]
	v_pk_fma_f32 v[84:85], v[100:101], v[84:85], v[92:93]
	v_lshl_add_u64 v[92:93], v[80:81], 1, v[144:145]
	v_cvt_pk_bf16_f32 v80, v114, v115
	v_cvt_pk_bf16_f32 v81, v116, v117
	v_cvt_pk_bf16_f32 v82, v118, v119
	v_cvt_pk_bf16_f32 v83, v120, v121
	ds_write_b128 v246, v[80:83]
	v_lshl_add_u64 v[240:241], v[92:93], 0, v[250:251]
	ds_read_b128 v[232:235], v247
	s_waitcnt lgkmcnt(0)
	global_store_dwordx4 v[240:241], v[232:235], off
	v_or_b32_e32 v104, 48, v158
	s_nop 0
	v_cvt_pk_bf16_f32 v80, v84, v85
	v_cvt_pk_bf16_f32 v81, v86, v87
	v_cvt_pk_bf16_f32 v82, v88, v89
	v_cvt_pk_bf16_f32 v83, v90, v91
	ds_write_b128 v246, v[80:83]
	v_lshl_add_u64 v[240:241], v[92:93], 0, v[250:251]
	ds_read_b128 v[232:235], v247
	s_waitcnt lgkmcnt(0)
	global_store_dwordx4 v[240:241], v[232:235], off offset:64
	s_nop 1
	v_add_u32_e32 v80, s2, v104
	v_ashrrev_i32_e32 v81, 31, v80
	v_lshl_add_u64 v[80:81], v[80:81], 2, s[4:5]
	global_load_dword v80, v[80:81], off
	s_waitcnt vmcnt(0)
; DI u32x4 pack8(f32x4 a, f32x4 b) { u32x4 w; w.x = cvtpk(a[0], a[1]); w.y = cvtpk(a[2], a[3]); w.z = cvtpk(b[0], b[1]); w.w = cvtpk(b[2], b[3]); return w; }
;   DI void operator()(const f32x4 (&acc)[2][2][4][2], const Unit& u, int wr, int wc, int fr, int fq) const {
;     ...
; #pragma unroll
;       for (int ai = 0; ai < 2; ++ai)
; #pragma unroll
;         for (int m = 0; m < 4; ++m) {
;           const int rowl = rowl0 + ai * 128 + m * 16; const int t = rowl & (SEQ - 1);
;           const float rstd = rsqrtf(ssq[row_off + rowl] * (1.f / DM) + EPSN) * sc;
;           const float* rc = rope + t * 32 + 8 * fq;
;           const f32x4 c0 = *(const f32x4*)(rc), c1 = *(const f32x4*)(rc + 4), s0 = *(const f32x4*)(rc + 65536), s1 = *(const f32x4*)(rc + 65536 + 4);
;           const f32x4 x1a = acc[ai][0][m][0] * rstd, x1b = acc[ai][0][m][1] * rstd, x2a = acc[ai][1][m][0] * rstd, x2b = acc[ai][1][m][1] * rstd;
;           const f32x4 o1a = x1a * c0 - x2a * s0, o1b = x1b * c1 - x2b * s1, o2a = x2a * c0 + x1a * s0, o2b = x2b * c1 + x1b * s1;
;           bf16_t* d = dst + (size_t)rowl * pitch + colbase + 8 * fq;
;           *(u32x4*)(d) = pack8(o1a, o1b); *(u32x4*)(d + 32) = pack8(o2a, o2b);
;           asm volatile("" ::: "memory");
;         }
	v_fmamk_f32 v80, v80, 0x3a800000, v203
	v_cmp_gt_f32_e32 vcc, s82, v80
	v_mul_f32_e32 v81, 0x4b800000, v80
	s_nop 0
	v_cndmask_b32_e32 v80, v80, v81, vcc
	v_rsq_f32_e32 v80, v80
	s_nop 0
	v_mul_f32_e32 v81, 0x45800000, v80
	v_cndmask_b32_e32 v80, v80, v81, vcc
	v_mul_f32_e32 v96, s3, v80
	v_lshlrev_b32_e32 v80, 7, v104
	v_and_b32_e32 v80, 0x3ff80, v80
	v_mov_b32_e32 v81, v187
	v_lshl_add_u64 v[88:89], v[138:139], 0, v[80:81]
	global_load_dwordx4 v[80:83], v[88:89], off offset:16
	global_load_dwordx4 v[84:87], v[88:89], off
	v_lshl_add_u64 v[92:93], v[88:89], 0, s[14:15]
	v_add_co_u32_e32 v88, vcc, s0, v88
	v_pk_mul_f32 v[66:67], v[66:67], v[96:97] op_sel_hi:[1,0]
	s_nop 0
	v_addc_co_u32_e32 v89, vcc, 0, v89, vcc
	global_load_dwordx4 v[88:91], v[88:89], off
	s_nop 0
	global_load_dwordx4 v[92:95], v[92:93], off offset:16
	v_pk_mul_f32 v[64:65], v[64:65], v[96:97] op_sel_hi:[1,0]
	v_pk_mul_f32 v[72:73], v[72:73], v[96:97] op_sel_hi:[1,0]
	v_pk_mul_f32 v[74:75], v[74:75], v[96:97] op_sel_hi:[1,0]
	v_pk_mul_f32 v[70:71], v[70:71], v[96:97] op_sel_hi:[1,0]
	v_pk_mul_f32 v[68:69], v[68:69], v[96:97] op_sel_hi:[1,0]
	v_pk_mul_f32 v[76:77], v[76:77], v[96:97] op_sel_hi:[1,0]
	v_pk_mul_f32 v[78:79], v[78:79], v[96:97] op_sel_hi:[1,0]
	s_waitcnt vmcnt(1)
	v_pk_mul_f32 v[96:97], v[88:89], v[68:69]
	s_waitcnt vmcnt(0)
	v_pk_mul_f32 v[100:101], v[92:93], v[64:65]
	v_pk_mul_f32 v[102:103], v[94:95], v[66:67]
	v_pk_fma_f32 v[100:101], v[80:81], v[72:73], v[100:101] neg_lo:[0,0,1] neg_hi:[0,0,1]
	v_pk_fma_f32 v[102:103], v[82:83], v[74:75], v[102:103] neg_lo:[0,0,1] neg_hi:[0,0,1]
	v_pk_mul_f32 v[72:73], v[92:93], v[72:73]
	v_pk_mul_f32 v[74:75], v[94:95], v[74:75]
	v_pk_mul_f32 v[98:99], v[90:91], v[70:71]
	v_pk_fma_f32 v[74:75], v[82:83], v[66:67], v[74:75]
	v_pk_fma_f32 v[72:73], v[80:81], v[64:65], v[72:73]
	v_mul_lo_u32 v66, s11, v104
	v_mad_u64_u32 v[64:65], s[12:13], s10, v104, 0
	v_pk_fma_f32 v[98:99], v[86:87], v[78:79], v[98:99] neg_lo:[0,0,1] neg_hi:[0,0,1]
	v_pk_fma_f32 v[96:97], v[84:85], v[76:77], v[96:97] neg_lo:[0,0,1] neg_hi:[0,0,1]
	v_pk_mul_f32 v[76:77], v[88:89], v[76:77]
	v_pk_mul_f32 v[78:79], v[90:91], v[78:79]
	v_add3_u32 v65, v65, v112, v66
	v_pk_fma_f32 v[70:71], v[86:87], v[70:71], v[78:79]
	v_pk_fma_f32 v[68:69], v[84:85], v[68:69], v[76:77]
	v_lshl_add_u64 v[76:77], v[64:65], 1, v[144:145]
	v_cvt_pk_bf16_f32 v64, v96, v97
	v_cvt_pk_bf16_f32 v65, v98, v99
	v_cvt_pk_bf16_f32 v66, v100, v101
	v_cvt_pk_bf16_f32 v67, v102, v103
	ds_write_b128 v246, v[64:67]
	v_lshl_add_u64 v[240:241], v[76:77], 0, v[250:251]
	ds_read_b128 v[232:235], v247
	s_waitcnt lgkmcnt(0)
	global_store_dwordx4 v[240:241], v[232:235], off
	v_add_u32_e32 v88, 0x80, v158
	s_nop 0
	v_cvt_pk_bf16_f32 v64, v68, v69
	v_cvt_pk_bf16_f32 v65, v70, v71
	v_cvt_pk_bf16_f32 v66, v72, v73
	v_cvt_pk_bf16_f32 v67, v74, v75
	ds_write_b128 v246, v[64:67]
	v_lshl_add_u64 v[240:241], v[76:77], 0, v[250:251]
	ds_read_b128 v[232:235], v247
	s_waitcnt lgkmcnt(0)
	global_store_dwordx4 v[240:241], v[232:235], off offset:64
	s_nop 1
	v_add_u32_e32 v64, s2, v88
	v_ashrrev_i32_e32 v65, 31, v64
	v_lshl_add_u64 v[64:65], v[64:65], 2, s[4:5]
	global_load_dword v64, v[64:65], off
	s_waitcnt vmcnt(0)
	v_fmamk_f32 v64, v64, 0x3a800000, v203
	v_cmp_gt_f32_e32 vcc, s82, v64
	v_mul_f32_e32 v65, 0x4b800000, v64
	s_nop 0
	v_cndmask_b32_e32 v64, v64, v65, vcc
	v_rsq_f32_e32 v64, v64
	s_nop 0
	v_mul_f32_e32 v65, 0x45800000, v64
	v_cndmask_b32_e32 v64, v64, v65, vcc
	v_mul_f32_e32 v80, s3, v64
	v_lshlrev_b32_e32 v64, 7, v88
	v_and_b32_e32 v64, 0x3e780, v64
	v_mov_b32_e32 v65, v187
	v_lshl_add_u64 v[72:73], v[138:139], 0, v[64:65]
	global_load_dwordx4 v[64:67], v[72:73], off offset:16
	global_load_dwordx4 v[68:71], v[72:73], off
	v_lshl_add_u64 v[76:77], v[72:73], 0, s[14:15]
	v_add_co_u32_e32 v72, vcc, s0, v72
	v_pk_mul_f32 v[48:49], v[48:49], v[80:81] op_sel_hi:[1,0]
	s_nop 0
	v_addc_co_u32_e32 v73, vcc, 0, v73, vcc
	global_load_dwordx4 v[72:75], v[72:73], off
	s_nop 0
	global_load_dwordx4 v[76:79], v[76:77], off offset:16
	v_pk_mul_f32 v[56:57], v[56:57], v[80:81] op_sel_hi:[1,0]
	v_pk_mul_f32 v[50:51], v[50:51], v[80:81] op_sel_hi:[1,0]
	v_pk_mul_f32 v[58:59], v[58:59], v[80:81] op_sel_hi:[1,0]
	v_pk_mul_f32 v[54:55], v[54:55], v[80:81] op_sel_hi:[1,0]
	v_pk_mul_f32 v[52:53], v[52:53], v[80:81] op_sel_hi:[1,0]
	v_pk_mul_f32 v[60:61], v[60:61], v[80:81] op_sel_hi:[1,0]
	v_pk_mul_f32 v[62:63], v[62:63], v[80:81] op_sel_hi:[1,0]
	s_waitcnt vmcnt(1)
	v_pk_mul_f32 v[80:81], v[72:73], v[52:53]
	s_waitcnt vmcnt(0)
	v_pk_mul_f32 v[84:85], v[76:77], v[48:49]
	v_pk_mul_f32 v[86:87], v[78:79], v[50:51]
	v_pk_fma_f32 v[84:85], v[64:65], v[56:57], v[84:85] neg_lo:[0,0,1] neg_hi:[0,0,1]
	v_pk_mul_f32 v[56:57], v[76:77], v[56:57]
	v_pk_fma_f32 v[86:87], v[66:67], v[58:59], v[86:87] neg_lo:[0,0,1] neg_hi:[0,0,1]
	v_pk_mul_f32 v[58:59], v[78:79], v[58:59]
	v_pk_fma_f32 v[56:57], v[64:65], v[48:49], v[56:57]
	v_ashrrev_i32_e32 v48, 31, v88
	v_pk_mul_f32 v[82:83], v[74:75], v[54:55]
	v_pk_fma_f32 v[58:59], v[66:67], v[50:51], v[58:59]
	v_mul_lo_u32 v50, s10, v48
	v_mul_lo_u32 v51, s11, v88
	v_mad_u64_u32 v[48:49], s[12:13], s10, v88, 0
	v_pk_fma_f32 v[82:83], v[70:71], v[62:63], v[82:83] neg_lo:[0,0,1] neg_hi:[0,0,1]
	v_pk_fma_f32 v[80:81], v[68:69], v[60:61], v[80:81] neg_lo:[0,0,1] neg_hi:[0,0,1]
	v_pk_mul_f32 v[60:61], v[72:73], v[60:61]
	v_pk_mul_f32 v[62:63], v[74:75], v[62:63]
	v_add3_u32 v49, v49, v50, v51
	v_pk_fma_f32 v[54:55], v[70:71], v[54:55], v[62:63]
	v_pk_fma_f32 v[52:53], v[68:69], v[52:53], v[60:61]
	v_lshl_add_u64 v[60:61], v[48:49], 1, v[144:145]
	v_cvt_pk_bf16_f32 v48, v80, v81
	v_cvt_pk_bf16_f32 v49, v82, v83
	v_cvt_pk_bf16_f32 v50, v84, v85
	v_cvt_pk_bf16_f32 v51, v86, v87
	ds_write_b128 v246, v[48:51]
	v_lshl_add_u64 v[240:241], v[60:61], 0, v[250:251]
	ds_read_b128 v[232:235], v247
	s_waitcnt lgkmcnt(0)
; DI u32x4 pack8(f32x4 a, f32x4 b) { u32x4 w; w.x = cvtpk(a[0], a[1]); w.y = cvtpk(a[2], a[3]); w.z = cvtpk(b[0], b[1]); w.w = cvtpk(b[2], b[3]); return w; }
;   DI void operator()(const f32x4 (&acc)[2][2][4][2], const Unit& u, int wr, int wc, int fr, int fq) const {
;     ...
; #pragma unroll
;       for (int ai = 0; ai < 2; ++ai)
; #pragma unroll
;         for (int m = 0; m < 4; ++m) {
;           const int rowl = rowl0 + ai * 128 + m * 16; const int t = rowl & (SEQ - 1);
;           const float rstd = rsqrtf(ssq[row_off + rowl] * (1.f / DM) + EPSN) * sc;
;           const float* rc = rope + t * 32 + 8 * fq;
;           const f32x4 c0 = *(const f32x4*)(rc), c1 = *(const f32x4*)(rc + 4), s0 = *(const f32x4*)(rc + 65536), s1 = *(const f32x4*)(rc + 65536 + 4);
;           const f32x4 x1a = acc[ai][0][m][0] * rstd, x1b = acc[ai][0][m][1] * rstd, x2a = acc[ai][1][m][0] * rstd, x2b = acc[ai][1][m][1] * rstd;
;           const f32x4 o1a = x1a * c0 - x2a * s0, o1b = x1b * c1 - x2b * s1, o2a = x2a * c0 + x1a * s0, o2b = x2b * c1 + x1b * s1;
;           bf16_t* d = dst + (size_t)rowl * pitch + colbase + 8 * fq;
;           *(u32x4*)(d) = pack8(o1a, o1b); *(u32x4*)(d + 32) = pack8(o2a, o2b);
;           asm volatile("" ::: "memory");
;         }
	global_store_dwordx4 v[240:241], v[232:235], off
	v_add_u32_e32 v72, 0x90, v158
	s_nop 0
	v_cvt_pk_bf16_f32 v48, v52, v53
	v_cvt_pk_bf16_f32 v49, v54, v55
	v_cvt_pk_bf16_f32 v50, v56, v57
	v_cvt_pk_bf16_f32 v51, v58, v59
	ds_write_b128 v246, v[48:51]
	v_lshl_add_u64 v[240:241], v[60:61], 0, v[250:251]
	ds_read_b128 v[232:235], v247
	s_waitcnt lgkmcnt(0)
	global_store_dwordx4 v[240:241], v[232:235], off offset:64
	s_nop 1
	v_add_u32_e32 v48, s2, v72
	v_ashrrev_i32_e32 v49, 31, v48
	v_lshl_add_u64 v[48:49], v[48:49], 2, s[4:5]
	global_load_dword v48, v[48:49], off
	s_waitcnt vmcnt(0)
	v_fmamk_f32 v48, v48, 0x3a800000, v203
	v_cmp_gt_f32_e32 vcc, s82, v48
	v_mul_f32_e32 v49, 0x4b800000, v48
	s_nop 0
	v_cndmask_b32_e32 v48, v48, v49, vcc
	v_rsq_f32_e32 v48, v48
	s_nop 0
	v_mul_f32_e32 v49, 0x45800000, v48
	v_cndmask_b32_e32 v48, v48, v49, vcc
	v_mul_f32_e32 v64, s3, v48
	v_lshlrev_b32_e32 v48, 7, v72
	v_and_b32_e32 v48, 0x3ef80, v48
	v_mov_b32_e32 v49, v187
	v_lshl_add_u64 v[56:57], v[138:139], 0, v[48:49]
	global_load_dwordx4 v[48:51], v[56:57], off offset:16
	global_load_dwordx4 v[52:55], v[56:57], off
	v_lshl_add_u64 v[60:61], v[56:57], 0, s[14:15]
	v_add_co_u32_e32 v56, vcc, s0, v56
	v_pk_mul_f32 v[32:33], v[32:33], v[64:65] op_sel_hi:[1,0]
	s_nop 0
	v_addc_co_u32_e32 v57, vcc, 0, v57, vcc
	global_load_dwordx4 v[56:59], v[56:57], off
	s_nop 0
	global_load_dwordx4 v[60:63], v[60:61], off offset:16
	v_pk_mul_f32 v[40:41], v[40:41], v[64:65] op_sel_hi:[1,0]
	v_pk_mul_f32 v[34:35], v[34:35], v[64:65] op_sel_hi:[1,0]
	v_pk_mul_f32 v[42:43], v[42:43], v[64:65] op_sel_hi:[1,0]
	v_pk_mul_f32 v[38:39], v[38:39], v[64:65] op_sel_hi:[1,0]
	v_pk_mul_f32 v[36:37], v[36:37], v[64:65] op_sel_hi:[1,0]
	v_pk_mul_f32 v[44:45], v[44:45], v[64:65] op_sel_hi:[1,0]
	v_pk_mul_f32 v[46:47], v[46:47], v[64:65] op_sel_hi:[1,0]
	s_waitcnt vmcnt(1)
	v_pk_mul_f32 v[64:65], v[56:57], v[36:37]
	s_waitcnt vmcnt(0)
	v_pk_mul_f32 v[68:69], v[60:61], v[32:33]
	v_pk_mul_f32 v[70:71], v[62:63], v[34:35]
	v_pk_fma_f32 v[68:69], v[48:49], v[40:41], v[68:69] neg_lo:[0,0,1] neg_hi:[0,0,1]
	v_pk_mul_f32 v[40:41], v[60:61], v[40:41]
	v_pk_fma_f32 v[70:71], v[50:51], v[42:43], v[70:71] neg_lo:[0,0,1] neg_hi:[0,0,1]
	v_pk_mul_f32 v[42:43], v[62:63], v[42:43]
	v_pk_fma_f32 v[40:41], v[48:49], v[32:33], v[40:41]
	v_ashrrev_i32_e32 v32, 31, v72
	v_pk_mul_f32 v[66:67], v[58:59], v[38:39]
	v_pk_fma_f32 v[42:43], v[50:51], v[34:35], v[42:43]
	v_mul_lo_u32 v34, s10, v32
	v_mul_lo_u32 v35, s11, v72
	v_mad_u64_u32 v[32:33], s[12:13], s10, v72, 0
	v_pk_fma_f32 v[66:67], v[54:55], v[46:47], v[66:67] neg_lo:[0,0,1] neg_hi:[0,0,1]
	v_pk_fma_f32 v[64:65], v[52:53], v[44:45], v[64:65] neg_lo:[0,0,1] neg_hi:[0,0,1]
	v_pk_mul_f32 v[44:45], v[56:57], v[44:45]
	v_pk_mul_f32 v[46:47], v[58:59], v[46:47]
	v_add3_u32 v33, v33, v34, v35
	v_pk_fma_f32 v[38:39], v[54:55], v[38:39], v[46:47]
	v_pk_fma_f32 v[36:37], v[52:53], v[36:37], v[44:45]
	v_lshl_add_u64 v[44:45], v[32:33], 1, v[144:145]
	v_cvt_pk_bf16_f32 v32, v64, v65
	v_cvt_pk_bf16_f32 v33, v66, v67
	v_cvt_pk_bf16_f32 v34, v68, v69
	v_cvt_pk_bf16_f32 v35, v70, v71
	ds_write_b128 v246, v[32:35]
	v_lshl_add_u64 v[240:241], v[44:45], 0, v[250:251]
	ds_read_b128 v[232:235], v247
	s_waitcnt lgkmcnt(0)
	global_store_dwordx4 v[240:241], v[232:235], off
	v_add_u32_e32 v56, 0xa0, v158
	s_nop 0
	v_cvt_pk_bf16_f32 v32, v36, v37
	v_cvt_pk_bf16_f32 v33, v38, v39
	v_cvt_pk_bf16_f32 v34, v40, v41
	v_cvt_pk_bf16_f32 v35, v42, v43
	ds_write_b128 v246, v[32:35]
	v_lshl_add_u64 v[240:241], v[44:45], 0, v[250:251]
	ds_read_b128 v[232:235], v247
	s_waitcnt lgkmcnt(0)
	global_store_dwordx4 v[240:241], v[232:235], off offset:64
	s_nop 1
	v_add_u32_e32 v32, s2, v56
	v_ashrrev_i32_e32 v33, 31, v32
	v_lshl_add_u64 v[32:33], v[32:33], 2, s[4:5]
	global_load_dword v32, v[32:33], off
	s_waitcnt vmcnt(0)
	v_fmamk_f32 v32, v32, 0x3a800000, v203
	v_cmp_gt_f32_e32 vcc, s82, v32
	v_mul_f32_e32 v33, 0x4b800000, v32
	s_nop 0
	v_cndmask_b32_e32 v32, v32, v33, vcc
	v_rsq_f32_e32 v32, v32
	s_nop 0
	v_mul_f32_e32 v33, 0x45800000, v32
	v_cndmask_b32_e32 v32, v32, v33, vcc
	v_mul_f32_e32 v48, s3, v32
	v_lshlrev_b32_e32 v32, 7, v56
	v_and_b32_e32 v32, 0x3f780, v32
	v_mov_b32_e32 v33, v187
	v_lshl_add_u64 v[40:41], v[138:139], 0, v[32:33]
	global_load_dwordx4 v[32:35], v[40:41], off offset:16
	global_load_dwordx4 v[36:39], v[40:41], off
	v_lshl_add_u64 v[44:45], v[40:41], 0, s[14:15]
	v_add_co_u32_e32 v40, vcc, s0, v40
	v_pk_mul_f32 v[16:17], v[16:17], v[48:49] op_sel_hi:[1,0]
	s_nop 0
	v_addc_co_u32_e32 v41, vcc, 0, v41, vcc
	global_load_dwordx4 v[40:43], v[40:41], off
	s_nop 0
	global_load_dwordx4 v[44:47], v[44:45], off offset:16
	v_pk_mul_f32 v[24:25], v[24:25], v[48:49] op_sel_hi:[1,0]
	v_pk_mul_f32 v[18:19], v[18:19], v[48:49] op_sel_hi:[1,0]
	v_pk_mul_f32 v[26:27], v[26:27], v[48:49] op_sel_hi:[1,0]
	v_pk_mul_f32 v[22:23], v[22:23], v[48:49] op_sel_hi:[1,0]
	v_pk_mul_f32 v[20:21], v[20:21], v[48:49] op_sel_hi:[1,0]
	v_pk_mul_f32 v[28:29], v[28:29], v[48:49] op_sel_hi:[1,0]
	v_pk_mul_f32 v[30:31], v[30:31], v[48:49] op_sel_hi:[1,0]
	s_waitcnt vmcnt(1)
; DI u32x4 pack8(f32x4 a, f32x4 b) { u32x4 w; w.x = cvtpk(a[0], a[1]); w.y = cvtpk(a[2], a[3]); w.z = cvtpk(b[0], b[1]); w.w = cvtpk(b[2], b[3]); return w; }
;   DI void operator()(const f32x4 (&acc)[2][2][4][2], const Unit& u, int wr, int wc, int fr, int fq) const {
;     ...
; #pragma unroll
;       for (int ai = 0; ai < 2; ++ai)
; #pragma unroll
;         for (int m = 0; m < 4; ++m) {
;           const int rowl = rowl0 + ai * 128 + m * 16; const int t = rowl & (SEQ - 1);
;           const float rstd = rsqrtf(ssq[row_off + rowl] * (1.f / DM) + EPSN) * sc;
;           const float* rc = rope + t * 32 + 8 * fq;
;           const f32x4 c0 = *(const f32x4*)(rc), c1 = *(const f32x4*)(rc + 4), s0 = *(const f32x4*)(rc + 65536), s1 = *(const f32x4*)(rc + 65536 + 4);
;           const f32x4 x1a = acc[ai][0][m][0] * rstd, x1b = acc[ai][0][m][1] * rstd, x2a = acc[ai][1][m][0] * rstd, x2b = acc[ai][1][m][1] * rstd;
;           const f32x4 o1a = x1a * c0 - x2a * s0, o1b = x1b * c1 - x2b * s1, o2a = x2a * c0 + x1a * s0, o2b = x2b * c1 + x1b * s1;
;           bf16_t* d = dst + (size_t)rowl * pitch + colbase + 8 * fq;
;           *(u32x4*)(d) = pack8(o1a, o1b); *(u32x4*)(d + 32) = pack8(o2a, o2b);
;           asm volatile("" ::: "memory");
;         }
	v_pk_mul_f32 v[48:49], v[40:41], v[20:21]
	s_waitcnt vmcnt(0)
	v_pk_mul_f32 v[52:53], v[44:45], v[16:17]
	v_pk_mul_f32 v[54:55], v[46:47], v[18:19]
	v_pk_fma_f32 v[52:53], v[32:33], v[24:25], v[52:53] neg_lo:[0,0,1] neg_hi:[0,0,1]
	v_pk_mul_f32 v[24:25], v[44:45], v[24:25]
	v_pk_fma_f32 v[54:55], v[34:35], v[26:27], v[54:55] neg_lo:[0,0,1] neg_hi:[0,0,1]
	v_pk_mul_f32 v[26:27], v[46:47], v[26:27]
	v_pk_fma_f32 v[24:25], v[32:33], v[16:17], v[24:25]
	v_ashrrev_i32_e32 v16, 31, v56
	v_pk_mul_f32 v[50:51], v[42:43], v[22:23]
	v_pk_fma_f32 v[26:27], v[34:35], v[18:19], v[26:27]
	v_mul_lo_u32 v18, s10, v16
	v_mul_lo_u32 v19, s11, v56
	v_mad_u64_u32 v[16:17], s[12:13], s10, v56, 0
	v_pk_fma_f32 v[50:51], v[38:39], v[30:31], v[50:51] neg_lo:[0,0,1] neg_hi:[0,0,1]
	v_pk_fma_f32 v[48:49], v[36:37], v[28:29], v[48:49] neg_lo:[0,0,1] neg_hi:[0,0,1]
	v_pk_mul_f32 v[28:29], v[40:41], v[28:29]
	v_pk_mul_f32 v[30:31], v[42:43], v[30:31]
	v_add3_u32 v17, v17, v18, v19
	v_pk_fma_f32 v[22:23], v[38:39], v[22:23], v[30:31]
	v_pk_fma_f32 v[20:21], v[36:37], v[20:21], v[28:29]
	v_lshl_add_u64 v[28:29], v[16:17], 1, v[144:145]
	v_cvt_pk_bf16_f32 v16, v48, v49
	v_cvt_pk_bf16_f32 v17, v50, v51
	v_cvt_pk_bf16_f32 v18, v52, v53
	v_cvt_pk_bf16_f32 v19, v54, v55
	ds_write_b128 v246, v[16:19]
	v_lshl_add_u64 v[240:241], v[28:29], 0, v[250:251]
	ds_read_b128 v[232:235], v247
	s_waitcnt lgkmcnt(0)
	global_store_dwordx4 v[240:241], v[232:235], off
	v_add_u32_e32 v44, 0xb0, v158
	s_nop 0
	v_cvt_pk_bf16_f32 v16, v20, v21
	v_cvt_pk_bf16_f32 v17, v22, v23
	v_cvt_pk_bf16_f32 v18, v24, v25
	v_cvt_pk_bf16_f32 v19, v26, v27
	ds_write_b128 v246, v[16:19]
	v_lshl_add_u64 v[240:241], v[28:29], 0, v[250:251]
	ds_read_b128 v[232:235], v247
	s_waitcnt lgkmcnt(0)
	global_store_dwordx4 v[240:241], v[232:235], off offset:64
	s_nop 1
	v_add_u32_e32 v16, s2, v44
	v_ashrrev_i32_e32 v17, 31, v16
	v_lshl_add_u64 v[16:17], v[16:17], 2, s[4:5]
	global_load_dword v16, v[16:17], off
	s_waitcnt vmcnt(0)
	v_fmamk_f32 v16, v16, 0x3a800000, v203
	v_cmp_gt_f32_e32 vcc, s82, v16
	v_mul_f32_e32 v17, 0x4b800000, v16
	s_nop 0
	v_cndmask_b32_e32 v16, v16, v17, vcc
	v_rsq_f32_e32 v16, v16
	s_nop 0
	v_mul_f32_e32 v17, 0x45800000, v16
	v_cndmask_b32_e32 v16, v16, v17, vcc
	v_mul_f32_e32 v32, s3, v16
	v_lshlrev_b32_e32 v16, 7, v44
	v_and_b32_e32 v16, 0x3ff80, v16
	v_mov_b32_e32 v17, v187
	v_lshl_add_u64 v[24:25], v[138:139], 0, v[16:17]
	global_load_dwordx4 v[16:19], v[24:25], off offset:16
	global_load_dwordx4 v[20:23], v[24:25], off
	v_lshl_add_u64 v[28:29], v[24:25], 0, s[14:15]
	v_add_co_u32_e32 v24, vcc, s0, v24
	v_pk_mul_f32 v[4:5], v[4:5], v[32:33] op_sel_hi:[1,0]
	s_nop 0
	v_addc_co_u32_e32 v25, vcc, 0, v25, vcc
	global_load_dwordx4 v[24:27], v[24:25], off
	s_nop 0
	global_load_dwordx4 v[28:31], v[28:29], off offset:16
	v_pk_mul_f32 v[34:35], v[12:13], v[32:33] op_sel_hi:[1,0]
	v_pk_mul_f32 v[36:37], v[14:15], v[32:33] op_sel_hi:[1,0]
	v_pk_mul_f32 v[38:39], v[8:9], v[32:33] op_sel_hi:[1,0]
	v_pk_mul_f32 v[40:41], v[10:11], v[32:33] op_sel_hi:[1,0]
	v_pk_mul_f32 v[6:7], v[6:7], v[32:33] op_sel_hi:[1,0]
	v_pk_mul_f32 v[42:43], v[2:3], v[32:33] op_sel_hi:[1,0]
	v_pk_mul_f32 v[32:33], v[0:1], v[32:33] op_sel_hi:[1,0]
	s_waitcnt vmcnt(1)
	v_pk_mul_f32 v[0:1], v[24:25], v[4:5]
	v_pk_mul_f32 v[2:3], v[26:27], v[6:7]
	v_pk_fma_f32 v[10:11], v[20:21], v[34:35], v[0:1] neg_lo:[0,0,1] neg_hi:[0,0,1]
	s_waitcnt vmcnt(0)
	v_pk_mul_f32 v[0:1], v[28:29], v[32:33]
	v_pk_fma_f32 v[8:9], v[22:23], v[36:37], v[2:3] neg_lo:[0,0,1] neg_hi:[0,0,1]
	v_pk_mul_f32 v[2:3], v[30:31], v[42:43]
	v_pk_fma_f32 v[14:15], v[16:17], v[38:39], v[0:1] neg_lo:[0,0,1] neg_hi:[0,0,1]
	v_pk_mul_f32 v[0:1], v[26:27], v[36:37]
	v_pk_fma_f32 v[12:13], v[18:19], v[40:41], v[2:3] neg_lo:[0,0,1] neg_hi:[0,0,1]
	v_pk_mul_f32 v[2:3], v[24:25], v[34:35]
	v_pk_fma_f32 v[0:1], v[22:23], v[6:7], v[0:1]
	v_pk_mul_f32 v[6:7], v[28:29], v[38:39]
	v_pk_fma_f32 v[2:3], v[20:21], v[4:5], v[2:3]
	v_pk_mul_f32 v[4:5], v[30:31], v[40:41]
	v_pk_fma_f32 v[6:7], v[16:17], v[32:33], v[6:7]
	v_ashrrev_i32_e32 v16, 31, v44
	v_pk_fma_f32 v[4:5], v[18:19], v[42:43], v[4:5]
	v_mul_lo_u32 v18, s10, v16
	v_mul_lo_u32 v19, s11, v44
	v_mad_u64_u32 v[16:17], s[10:11], s10, v44, 0
	v_add3_u32 v17, v17, v18, v19
	v_lshl_add_u64 v[20:21], v[16:17], 1, v[144:145]
	v_cvt_pk_bf16_f32 v16, v10, v11
	v_cvt_pk_bf16_f32 v17, v8, v9
	v_cvt_pk_bf16_f32 v18, v14, v15
	v_cvt_pk_bf16_f32 v19, v12, v13
	v_cvt_pk_bf16_f32 v8, v2, v3
	v_cvt_pk_bf16_f32 v9, v0, v1
	v_cvt_pk_bf16_f32 v10, v6, v7
	v_cvt_pk_bf16_f32 v11, v4, v5
	ds_write_b128 v246, v[16:19]
	v_lshl_add_u64 v[240:241], v[20:21], 0, v[250:251]
	ds_read_b128 v[232:235], v247
	s_waitcnt lgkmcnt(0)
	global_store_dwordx4 v[240:241], v[232:235], off
	ds_write_b128 v246, v[8:11]
	v_lshl_add_u64 v[240:241], v[20:21], 0, v[250:251]
	ds_read_b128 v[232:235], v247
	s_waitcnt lgkmcnt(0)
	global_store_dwordx4 v[240:241], v[232:235], off offset:64
	s_andn2_b64 vcc, exec, s[8:9]
	s_mov_b64 s[8:9], -1
	s_cbranch_vccnz .LBB0_620
